# attention row-max: 16-deep dependent v_max3 chain split into two independent chains (exact same max)
# baseline (speedup 1.0000x reference)
; DI f32x16 mfma32(bf16x8 a, bf16x8 b, f32x16 c) { return __builtin_amdgcn_mfma_f32_32x32x16_bf16(a, b, c, 0, 0, 0); }
; template <int MODE>
; DI void attn_unit(char* lds, const Params& p, int layer, int u) {
;     ...
;     if (t + 1 < NT) { stage(lds + ((t + 1) & 1) * BUFSZ); if (t + 2 < NT) prefetch(t + 2); }
;     const int key0 = (MODE == 3) ? q0 - 64 + 64 * t : 64 * (tlo + t);
;     const bool act = (MODE != 3) || (t >= (wid >> 1) && t <= (wid >> 1) + 2);
;     if (act) {
;       f32x16 S0 = zero16(), S1 = zero16();
;       const char* kb = cur + lr * KST + (MODE == 0 ? comp * 64 : 0) + lh * 16;
; #pragma unroll
;       for (int ks = 0; ks < NKS; ++ks) {
;         const bf16x8 k0 = *(const bf16x8*)(kb + ks * 32), k1 = *(const bf16x8*)(kb + 32 * KST + ks * 32);
;         S0 = mfma32(k0, qf[ks], S0); S1 = mfma32(k1, qf[ks], S1);
;       }
;       float aoff = 0.f;
;       if (MODE == 0) {
;         const float dbase = (float)(key0 + 4 * lh - qrow);
;         if (key0 > qlo + 31) { S0 = S0 - T0; S1 = S1 - T1; aoff = -slope2 * dbase; }
;         else if (key0 + 63 < qlo) { S0 = S0 + T0; S1 = S1 + T1; aoff = slope2 * dbase; }
;         else {
; #pragma unroll
;           for (int r = 0; r < 16; ++r) { const float cc = (float)((r & 3) + 8 * (r >> 2));
;             S0[r] = fmaf(-slope2, fabsf(dbase + cc), S0[r]); S1[r] = fmaf(-slope2, fabsf(dbase + cc + 32.f), S1[r]); }
;         }
;       }
;       if (MODE == 3) {
;         const int rel0 = key0 + 4 * lh - qrow;
; #pragma unroll
;         for (int r = 0; r < 16; ++r) { const int cc = (r & 3) + 8 * (r >> 2);
;           { const int rel = rel0 + cc, v = qrow + rel; const bool ok = (rel >= -64) && (rel <= 64) && (v >= 0) && (v < L); S0[r] = ok ? fmaf(-slope2, fabsf((float)rel), S0[r]) : -1e30f; }
;           { const int rel = rel0 + cc + 32, v = qrow + rel; const bool ok = (rel >= -64) && (rel <= 64) && (v >= 0) && (v < L); S1[r] = ok ? fmaf(-slope2, fabsf((float)rel), S1[r]) : -1e30f; } }
;       }
;       float mx = fmaxf(S0[0], S1[0]);
; #pragma unroll
;       for (int r = 1; r < 16; ++r) mx = max3f(mx, S0[r], S1[r]);
;       mx += aoff;
;       if (__any(mx > m + 8.f)) {
;         mx = fmaxf(mx, __shfl_xor(mx, 32));
;         const float mnew = fmaxf(m, mx);
;         const float al = __builtin_amdgcn_exp2f(m - mnew); l *= al; O0 *= al; O1 *= al;
;         m = mnew;
;       }
.LBB0_586:
	s_bitcmp1_b32 s1, 0
	s_cselect_b32 s4, 0, 0x4800
	s_cselect_b32 s33, 0x4800, 0
	v_add_u32_e32 v32, s33, v94
	v_add_u32_e32 v102, s4, v100
	s_waitcnt vmcnt(1)
	ds_write_b128 v32, v[84:87]
	s_waitcnt vmcnt(0)
	ds_write_b128 v32, v[80:83] offset:9216
	v_add_u32_e32 v90, v102, v92
	ds_read_b128 v[32:35], v90
	ds_read_b128 v[104:107], v90 offset:32
	v_mad_i64_i32 v[80:81], s[50:51], v101, s72, v[96:97]
	ds_read_b128 v[48:51], v90 offset:4608
	global_load_dwordx4 v[84:87], v[80:81], off offset:3328
	s_nop 0
	global_load_dwordx4 v[80:83], v[98:99], off
	s_waitcnt lgkmcnt(2)
	v_mfma_f32_32x32x16_bf16 v[32:47], v[32:35], v[76:79], 0
	s_waitcnt lgkmcnt(1)
	v_mfma_f32_32x32x16_bf16 v[32:47], v[104:107], v[72:75], v[32:47]
	ds_read_b128 v[104:107], v90 offset:4640
	s_waitcnt lgkmcnt(1)
	v_mfma_f32_32x32x16_bf16 v[48:63], v[48:51], v[76:79], 0
	s_waitcnt lgkmcnt(0)
	v_mfma_f32_32x32x16_bf16 v[48:63], v[104:107], v[72:75], v[48:63]
	ds_read_b128 v[104:107], v90 offset:64
	s_waitcnt lgkmcnt(0)
	v_mfma_f32_32x32x16_bf16 v[32:47], v[104:107], v[68:71], v[32:47]
	ds_read_b128 v[104:107], v90 offset:4672
	s_waitcnt lgkmcnt(0)
	v_mfma_f32_32x32x16_bf16 v[48:63], v[104:107], v[68:71], v[48:63]
	ds_read_b128 v[104:107], v90 offset:4704
	s_waitcnt lgkmcnt(0)
	v_mfma_f32_32x32x16_bf16 v[48:63], v[104:107], v[64:67], v[48:63]
	ds_read_b128 v[104:107], v90 offset:96
	s_waitcnt lgkmcnt(0)
	v_mfma_f32_32x32x16_bf16 v[32:47], v[104:107], v[64:67], v[32:47]
	s_nop 8
	v_max_f32_e32 v90, v48, v48
	s_nop 1
	v_max_f32_e32 v91, v32, v32
	v_max_f32_e32 v90, v91, v90
	v_max3_f32 v90, v90, v33, v49
	v_add_f32_e32 v91, 0x41000000, v93
	v_max_f32_e32 v246, v34, v50
	v_max3_f32 v90, v90, v35, v51
	v_max3_f32 v246, v246, v36, v52
	v_max3_f32 v90, v90, v37, v53
	v_max3_f32 v246, v246, v38, v54
	v_max3_f32 v90, v90, v39, v55
	v_max3_f32 v246, v246, v40, v56
	v_max3_f32 v90, v90, v41, v57
	v_max3_f32 v246, v246, v42, v58
	v_max3_f32 v90, v90, v43, v59
	v_max3_f32 v246, v246, v44, v60
	v_max3_f32 v90, v90, v45, v61
	v_max3_f32 v246, v246, v46, v62
	v_max3_f32 v90, v90, v47, v63
	v_max_f32_e32 v90, v90, v246
	v_cmp_gt_f32_e32 vcc, v90, v91
	s_cbranch_vccz .LBB0_585
	v_cmp_lt_i32_e32 vcc, v209, v208
	v_add_f32_e32 v90, 0, v90
	s_nop 0
	v_cndmask_b32_e32 v91, v207, v209, vcc
	v_lshlrev_b32_e32 v91, 2, v91
	ds_bpermute_b32 v91, v91, v90
	s_waitcnt lgkmcnt(0)
	v_max3_f32 v91, v93, v90, v91
	v_sub_f32_e32 v90, v93, v91
	v_exp_f32_e32 v90, v90
	v_mov_b32_e32 v93, v91
	v_mul_f32_e32 v95, v95, v90
	v_pk_mul_f32 v[14:15], v[14:15], v[90:91] op_sel_hi:[1,0]
	v_pk_mul_f32 v[12:13], v[12:13], v[90:91] op_sel_hi:[1,0]
	v_pk_mul_f32 v[10:11], v[10:11], v[90:91] op_sel_hi:[1,0]
	v_pk_mul_f32 v[8:9], v[8:9], v[90:91] op_sel_hi:[1,0]
	v_pk_mul_f32 v[6:7], v[6:7], v[90:91] op_sel_hi:[1,0]
	v_pk_mul_f32 v[4:5], v[4:5], v[90:91] op_sel_hi:[1,0]
	v_pk_mul_f32 v[2:3], v[2:3], v[90:91] op_sel_hi:[1,0]
	v_pk_mul_f32 v[0:1], v[0:1], v[90:91] op_sel_hi:[1,0]
	v_pk_mul_f32 v[30:31], v[30:31], v[90:91] op_sel_hi:[1,0]
	v_pk_mul_f32 v[28:29], v[28:29], v[90:91] op_sel_hi:[1,0]
	v_pk_mul_f32 v[26:27], v[26:27], v[90:91] op_sel_hi:[1,0]
	v_pk_mul_f32 v[24:25], v[24:25], v[90:91] op_sel_hi:[1,0]
	v_pk_mul_f32 v[22:23], v[22:23], v[90:91] op_sel_hi:[1,0]
	v_pk_mul_f32 v[20:21], v[20:21], v[90:91] op_sel_hi:[1,0]
	v_pk_mul_f32 v[18:19], v[18:19], v[90:91] op_sel_hi:[1,0]
	v_pk_mul_f32 v[16:17], v[16:17], v[90:91] op_sel_hi:[1,0]
	s_branch .LBB0_585
.LBB0_588:
	s_waitcnt vmcnt(1)
	ds_write_b128 v94, v[84:87] offset:18432
	s_waitcnt vmcnt(0)
	ds_write_b128 v94, v[80:83] offset:27648
	v_add_u32_e32 v82, v100, v92
	ds_read_b128 v[32:35], v82
	ds_read_b128 v[84:87], v82 offset:32
	ds_read_b128 v[48:51], v82 offset:4608
	v_add_f32_e32 v83, 0x41000000, v93
	s_waitcnt lgkmcnt(2)
	v_mfma_f32_32x32x16_bf16 v[32:47], v[32:35], v[76:79], 0
	s_waitcnt lgkmcnt(1)
	v_mfma_f32_32x32x16_bf16 v[32:47], v[84:87], v[72:75], v[32:47]
	ds_read_b128 v[84:87], v82 offset:4640
	s_waitcnt lgkmcnt(1)
	v_mfma_f32_32x32x16_bf16 v[48:63], v[48:51], v[76:79], 0
	s_waitcnt lgkmcnt(0)
	v_mfma_f32_32x32x16_bf16 v[48:63], v[84:87], v[72:75], v[48:63]
	ds_read_b128 v[84:87], v82 offset:64
	s_waitcnt lgkmcnt(0)
	v_mfma_f32_32x32x16_bf16 v[32:47], v[84:87], v[68:71], v[32:47]
	ds_read_b128 v[84:87], v82 offset:4672
	s_waitcnt lgkmcnt(0)
	v_mfma_f32_32x32x16_bf16 v[48:63], v[84:87], v[68:71], v[48:63]
	ds_read_b128 v[84:87], v82 offset:4704
	s_waitcnt lgkmcnt(0)
	v_mfma_f32_32x32x16_bf16 v[48:63], v[84:87], v[64:67], v[48:63]
	ds_read_b128 v[84:87], v82 offset:96
	s_waitcnt lgkmcnt(0)
	v_mfma_f32_32x32x16_bf16 v[32:47], v[84:87], v[64:67], v[32:47]
	s_nop 8
	v_max_f32_e32 v80, v48, v48
	s_nop 1
	v_max_f32_e32 v81, v32, v32
	v_max_f32_e32 v80, v81, v80
	v_max3_f32 v80, v80, v33, v49
	v_max_f32_e32 v246, v34, v50
	v_max3_f32 v80, v80, v35, v51
	v_max3_f32 v246, v246, v36, v52
	v_max3_f32 v80, v80, v37, v53
	v_max3_f32 v246, v246, v38, v54
	v_max3_f32 v80, v80, v39, v55
	v_max3_f32 v246, v246, v40, v56
	v_max3_f32 v80, v80, v41, v57
	v_max3_f32 v246, v246, v42, v58
	v_max3_f32 v80, v80, v43, v59
	v_max3_f32 v246, v246, v44, v60
	v_max3_f32 v80, v80, v45, v61
	v_max3_f32 v246, v246, v46, v62
	v_max3_f32 v80, v80, v47, v63
	v_max_f32_e32 v80, v80, v246
	v_cmp_gt_f32_e32 vcc, v80, v83
	s_cbranch_vccz .LBB0_590
	v_cmp_lt_i32_e32 vcc, v209, v208
	v_add_f32_e32 v80, 0, v80
	s_nop 0
	v_cndmask_b32_e32 v81, v207, v209, vcc
	v_lshlrev_b32_e32 v81, 2, v81
	ds_bpermute_b32 v81, v81, v80
	s_waitcnt lgkmcnt(0)
	v_max3_f32 v81, v93, v80, v81
	v_sub_f32_e32 v80, v93, v81
	v_exp_f32_e32 v80, v80
	v_sub_f32_e32 v90, 0, v81
	v_add_f32_e32 v83, 0x41000000, v81
	v_mov_b32_e32 v93, v81
	v_mul_f32_e32 v95, v95, v80
	v_pk_mul_f32 v[14:15], v[14:15], v[80:81] op_sel_hi:[1,0]
	v_pk_mul_f32 v[12:13], v[12:13], v[80:81] op_sel_hi:[1,0]
	v_pk_mul_f32 v[10:11], v[10:11], v[80:81] op_sel_hi:[1,0]
	v_pk_mul_f32 v[8:9], v[8:9], v[80:81] op_sel_hi:[1,0]
	v_pk_mul_f32 v[6:7], v[6:7], v[80:81] op_sel_hi:[1,0]
	v_pk_mul_f32 v[4:5], v[4:5], v[80:81] op_sel_hi:[1,0]
	v_pk_mul_f32 v[2:3], v[2:3], v[80:81] op_sel_hi:[1,0]
	v_pk_mul_f32 v[0:1], v[0:1], v[80:81] op_sel_hi:[1,0]
	v_pk_mul_f32 v[30:31], v[30:31], v[80:81] op_sel_hi:[1,0]
	v_pk_mul_f32 v[28:29], v[28:29], v[80:81] op_sel_hi:[1,0]
	v_pk_mul_f32 v[26:27], v[26:27], v[80:81] op_sel_hi:[1,0]
	v_pk_mul_f32 v[24:25], v[24:25], v[80:81] op_sel_hi:[1,0]
	v_pk_mul_f32 v[22:23], v[22:23], v[80:81] op_sel_hi:[1,0]
	v_pk_mul_f32 v[20:21], v[20:21], v[80:81] op_sel_hi:[1,0]
	v_pk_mul_f32 v[18:19], v[18:19], v[80:81] op_sel_hi:[1,0]
	v_pk_mul_f32 v[16:17], v[16:17], v[80:81] op_sel_hi:[1,0]
; template <int MODE>
; DI void attn_unit(char* lds, const Params& p, int layer, int u) {
;     ...
;       f32x16 S0 = zero16(), S1 = zero16();
;       const char* kb = cur + lr * KST + (MODE == 0 ? comp * 64 : 0) + lh * 16;
; #pragma unroll
;       for (int ks = 0; ks < NKS; ++ks) {
;         const bf16x8 k0 = *(const bf16x8*)(kb + ks * 32), k1 = *(const bf16x8*)(kb + 32 * KST + ks * 32);
;         S0 = mfma32(k0, qf[ks], S0); S1 = mfma32(k1, qf[ks], S1);
;       }
;       float aoff = 0.f;
;       if (MODE == 0) {
;     ...
;       { const f32x2 nm = {aoff - m, aoff - m};
; #pragma unroll
;         for (int r = 0; r < 8; ++r) {
;           f32x2 a = {S0[2 * r], S0[2 * r + 1]}, b = {S1[2 * r], S1[2 * r + 1]};
;           asm("v_pk_add_f32 %0, %1, %2" : "=v"(a) : "v"(a), "v"(nm));
;           asm("v_pk_add_f32 %0, %1, %2" : "=v"(b) : "v"(b), "v"(nm));
;           S0[2 * r] = a[0]; S0[2 * r + 1] = a[1]; S1[2 * r] = b[0]; S1[2 * r + 1] = b[1];
;         } }
; #pragma unroll
;       for (int r = 0; r < 16; ++r) { S0[r] = __builtin_amdgcn_exp2f(S0[r]); S1[r] = __builtin_amdgcn_exp2f(S1[r]); }
;       const f32x16 SS = S0 + S1;
;       float ps = 0.f;
; #pragma unroll
;       for (int r = 0; r < 16; ++r) ps += SS[r];
;       l += ps;
;       bf16x8 pf[4];
; #pragma unroll
;       for (int s = 0; s < 4; ++s) {
;         u32x4 w;
;         if (s < 2) { w[0] = pk2(S0[8 * s], S0[8 * s + 1]); w[1] = pk2(S0[8 * s + 2], S0[8 * s + 3]); w[2] = pk2(S0[8 * s + 4], S0[8 * s + 5]); w[3] = pk2(S0[8 * s + 6], S0[8 * s + 7]); }
;         else { const int s2 = s - 2; w[0] = pk2(S1[8 * s2], S1[8 * s2 + 1]); w[1] = pk2(S1[8 * s2 + 2], S1[8 * s2 + 3]); w[2] = pk2(S1[8 * s2 + 4], S1[8 * s2 + 5]); w[3] = pk2(S1[8 * s2 + 6], S1[8 * s2 + 7]); }
;         pf[s] = __builtin_bit_cast(bf16x8, w);
;       }
;       const char* vb = cur + VOFF + lr * VST + lh * 8;
; #pragma unroll
;       for (int s = 0; s < 4; ++s) {
;         { const s16x4 lo = *(const s16x4*)(vb + s * 32), hi = *(const s16x4*)(vb + s * 32 + 16);
;           O0 = mfma32(__builtin_shufflevector(lo, hi, 0, 1, 2, 3, 4, 5, 6, 7), pf[s], O0); }
;         { const s16x4 lo = *(const s16x4*)(vb + 32 * VST + s * 32), hi = *(const s16x4*)(vb + 32 * VST + s * 32 + 16);
;           O1 = mfma32(__builtin_shufflevector(lo, hi, 0, 1, 2, 3, 4, 5, 6, 7), pf[s], O1); }
;       }
;     }
;     __syncthreads();
.LBB0_590:
	v_mov_b32_e32 v91, v90
	v_pk_add_f32 v[32:33], v[32:33], v[90:91]
	v_pk_add_f32 v[48:49], v[48:49], v[90:91]
	v_pk_add_f32 v[34:35], v[34:35], v[90:91]
	v_pk_add_f32 v[50:51], v[50:51], v[90:91]
	v_pk_add_f32 v[36:37], v[36:37], v[90:91]
	v_pk_add_f32 v[52:53], v[52:53], v[90:91]
	s_nop 0
	v_exp_f32_e32 v32, v32
	v_exp_f32_e32 v80, v48
	v_exp_f32_e32 v33, v33
	v_exp_f32_e32 v81, v49
	v_exp_f32_e32 v34, v34
	v_exp_f32_e32 v50, v50
	v_exp_f32_e32 v35, v35
	v_exp_f32_e32 v51, v51
	v_exp_f32_e32 v36, v36
	v_exp_f32_e32 v52, v52
	v_exp_f32_e32 v37, v37
	v_exp_f32_e32 v53, v53
	v_pk_add_f32 v[106:107], v[32:33], v[80:81]
	v_pk_add_f32 v[38:39], v[38:39], v[90:91]
	v_pk_add_f32 v[54:55], v[54:55], v[90:91]
	v_pk_add_f32 v[104:105], v[34:35], v[50:51]
	v_add_f32_e32 v92, 0, v106
	v_exp_f32_e32 v38, v38
	v_exp_f32_e32 v54, v54
	v_exp_f32_e32 v39, v39
	v_exp_f32_e32 v55, v55
	v_add_f32_e32 v92, v107, v92
	v_pk_add_f32 v[40:41], v[40:41], v[90:91]
	v_pk_add_f32 v[56:57], v[56:57], v[90:91]
	v_add_f32_e32 v92, v104, v92
	v_exp_f32_e32 v40, v40
	v_exp_f32_e32 v56, v56
	v_exp_f32_e32 v41, v41
	v_exp_f32_e32 v57, v57
	v_pk_add_f32 v[102:103], v[36:37], v[52:53]
	v_add_f32_e32 v92, v105, v92
	v_pk_add_f32 v[42:43], v[42:43], v[90:91]
	v_pk_add_f32 v[58:59], v[58:59], v[90:91]
	v_add_f32_e32 v92, v102, v92
	v_exp_f32_e32 v42, v42
	v_exp_f32_e32 v58, v58
	v_exp_f32_e32 v43, v43
	v_exp_f32_e32 v59, v59
	v_pk_add_f32 v[98:99], v[38:39], v[54:55]
	v_add_f32_e32 v92, v103, v92
	v_pk_add_f32 v[60:61], v[60:61], v[90:91]
	v_add_f32_e32 v92, v98, v92
	v_pk_add_f32 v[44:45], v[44:45], v[90:91]
	v_exp_f32_e32 v60, v60
	v_exp_f32_e32 v84, v44
	v_exp_f32_e32 v85, v45
	v_exp_f32_e32 v61, v61
	v_pk_add_f32 v[96:97], v[40:41], v[56:57]
	v_add_f32_e32 v92, v99, v92
	v_pk_add_f32 v[62:63], v[62:63], v[90:91]
	v_add_f32_e32 v92, v96, v92
	v_pk_add_f32 v[46:47], v[46:47], v[90:91]
	v_exp_f32_e32 v62, v62
	v_exp_f32_e32 v86, v46
	v_exp_f32_e32 v87, v47
	v_exp_f32_e32 v63, v63
	v_pk_add_f32 v[48:49], v[42:43], v[58:59]
	v_add_f32_e32 v92, v97, v92
	v_add_f32_e32 v48, v48, v92
	v_pk_add_f32 v[46:47], v[84:85], v[60:61]
	v_add_f32_e32 v48, v49, v48
	v_add_f32_e32 v46, v46, v48
	v_pk_add_f32 v[44:45], v[86:87], v[62:63]
	v_add_f32_e32 v46, v47, v46
	v_add_f32_e32 v44, v44, v46
	v_cvt_pk_bf16_f32 v46, v36, v37
	v_cvt_pk_bf16_f32 v36, v80, v81
	v_add_u32_e32 v80, v100, v112
	v_add_u32_e32 v49, 0x2000, v80
	v_add_f32_e32 v48, v45, v44
	v_cvt_pk_bf16_f32 v44, v32, v33
	v_cvt_pk_bf16_f32 v47, v38, v39
	v_cvt_pk_bf16_f32 v37, v50, v51
	v_cvt_pk_bf16_f32 v38, v52, v53
	v_cvt_pk_bf16_f32 v39, v54, v55
	v_cvt_pk_bf16_f32 v32, v56, v57
	ds_read2_b64 v[50:53], v49 offset0:128 offset1:130
	ds_read2_b64 v[54:57], v49 offset0:132 offset1:134
	v_cvt_pk_bf16_f32 v45, v34, v35
	v_cvt_pk_bf16_f32 v33, v58, v59
	v_add_u32_e32 v58, 0x3000, v80
	s_waitcnt lgkmcnt(1)
	v_mfma_f32_32x32x16_bf16 v[0:15], v[50:53], v[44:47], v[0:15]
	ds_read2_b64 v[50:53], v58 offset0:192 offset1:194
	v_cvt_pk_bf16_f32 v40, v40, v41
	v_cvt_pk_bf16_f32 v41, v42, v43
	v_cvt_pk_bf16_f32 v42, v84, v85
	v_cvt_pk_bf16_f32 v43, v86, v87
	v_cvt_pk_bf16_f32 v34, v60, v61
	v_cvt_pk_bf16_f32 v35, v62, v63
	s_waitcnt lgkmcnt(0)
	v_mfma_f32_32x32x16_bf16 v[16:31], v[50:53], v[44:47], v[16:31]
	ds_read2_b64 v[44:47], v58 offset0:196 offset1:198
	v_add_f32_e32 v81, v95, v48
	v_mfma_f32_32x32x16_bf16 v[0:15], v[54:57], v[40:43], v[0:15]
	s_waitcnt lgkmcnt(0)
	v_mfma_f32_32x32x16_bf16 v[16:31], v[44:47], v[40:43], v[16:31]
	ds_read2_b64 v[40:43], v49 offset0:136 offset1:138
	s_waitcnt lgkmcnt(0)
	v_mfma_f32_32x32x16_bf16 v[0:15], v[40:43], v[36:39], v[0:15]
	ds_read2_b64 v[40:43], v58 offset0:200 offset1:202
	s_waitcnt lgkmcnt(0)
	v_mfma_f32_32x32x16_bf16 v[16:31], v[40:43], v[36:39], v[16:31]
	ds_read2_b64 v[36:39], v49 offset0:140 offset1:142
	s_waitcnt lgkmcnt(0)
	v_mfma_f32_32x32x16_bf16 v[0:15], v[36:39], v[32:35], v[0:15]
	ds_read2_b64 v[36:39], v58 offset0:204 offset1:206
	s_waitcnt lgkmcnt(0)
	s_barrier
	v_mfma_f32_32x32x16_bf16 v[16:31], v[36:39], v[32:35], v[16:31]
	ds_read_b128 v[84:87], v82 offset:23136
	ds_read_b128 v[94:97], v82 offset:18528
	ds_read_b128 v[98:101], v82 offset:23104
	ds_read_b128 v[102:105], v82 offset:18496
	ds_read_b128 v[106:109], v82 offset:23072
	ds_read_b128 v[32:35], v82 offset:18432
	ds_read_b128 v[116:119], v82 offset:18464
	ds_read_b128 v[48:51], v82 offset:23040
	s_waitcnt lgkmcnt(2)
	v_mfma_f32_32x32x16_bf16 v[32:47], v[32:35], v[76:79], 0
	s_waitcnt lgkmcnt(0)
	v_mfma_f32_32x32x16_bf16 v[48:63], v[48:51], v[76:79], 0
	v_mfma_f32_32x32x16_bf16 v[32:47], v[116:119], v[72:75], v[32:47]
	v_mfma_f32_32x32x16_bf16 v[48:63], v[106:109], v[72:75], v[48:63]
	v_mfma_f32_32x32x16_bf16 v[32:47], v[102:105], v[68:71], v[32:47]
	v_mfma_f32_32x32x16_bf16 v[48:63], v[98:101], v[68:71], v[48:63]
	v_mfma_f32_32x32x16_bf16 v[32:47], v[94:97], v[64:67], v[32:47]
	v_mfma_f32_32x32x16_bf16 v[48:63], v[84:87], v[64:67], v[48:63]
	s_nop 10
	v_max_f32_e32 v65, v32, v32
	v_max_f32_e32 v64, v48, v48
	v_max_f32_e32 v64, v65, v64
	v_max3_f32 v64, v64, v33, v49
	v_max_f32_e32 v246, v34, v50
	v_max3_f32 v64, v64, v35, v51
	v_max3_f32 v246, v246, v36, v52
	v_max3_f32 v64, v64, v37, v53
	v_max3_f32 v246, v246, v38, v54
	v_max3_f32 v64, v64, v39, v55
	v_max3_f32 v246, v246, v40, v56
	v_max3_f32 v64, v64, v41, v57
	v_max3_f32 v246, v246, v42, v58
	v_max3_f32 v64, v64, v43, v59
	v_max3_f32 v246, v246, v44, v60
	v_max3_f32 v64, v64, v45, v61
	v_max3_f32 v246, v246, v46, v62
	v_max3_f32 v64, v64, v47, v63
	v_max_f32_e32 v64, v64, v246
	v_cmp_gt_f32_e32 vcc, v64, v83
	s_cbranch_vccz .LBB0_592
	v_cmp_lt_i32_e32 vcc, v209, v208
	v_add_f32_e32 v64, 0, v64
	s_nop 0
	v_cndmask_b32_e32 v65, v207, v209, vcc
	v_lshlrev_b32_e32 v65, 2, v65
	ds_bpermute_b32 v65, v65, v64
	s_waitcnt lgkmcnt(0)
	v_max3_f32 v65, v93, v64, v65
	v_sub_f32_e32 v64, v93, v65
	v_exp_f32_e32 v64, v64
	v_sub_f32_e32 v90, 0, v65
	v_mov_b32_e32 v91, v90
	v_mul_f32_e32 v81, v81, v64
	v_pk_mul_f32 v[14:15], v[14:15], v[64:65] op_sel_hi:[1,0]
	v_pk_mul_f32 v[12:13], v[12:13], v[64:65] op_sel_hi:[1,0]
	v_pk_mul_f32 v[10:11], v[10:11], v[64:65] op_sel_hi:[1,0]
	v_pk_mul_f32 v[8:9], v[8:9], v[64:65] op_sel_hi:[1,0]
	v_pk_mul_f32 v[6:7], v[6:7], v[64:65] op_sel_hi:[1,0]
	v_pk_mul_f32 v[4:5], v[4:5], v[64:65] op_sel_hi:[1,0]
	v_pk_mul_f32 v[2:3], v[2:3], v[64:65] op_sel_hi:[1,0]
	v_pk_mul_f32 v[0:1], v[0:1], v[64:65] op_sel_hi:[1,0]
	v_pk_mul_f32 v[30:31], v[30:31], v[64:65] op_sel_hi:[1,0]
	v_pk_mul_f32 v[28:29], v[28:29], v[64:65] op_sel_hi:[1,0]
	v_pk_mul_f32 v[26:27], v[26:27], v[64:65] op_sel_hi:[1,0]
	v_pk_mul_f32 v[24:25], v[24:25], v[64:65] op_sel_hi:[1,0]
	v_pk_mul_f32 v[22:23], v[22:23], v[64:65] op_sel_hi:[1,0]
	v_pk_mul_f32 v[20:21], v[20:21], v[64:65] op_sel_hi:[1,0]
	v_pk_mul_f32 v[18:19], v[18:19], v[64:65] op_sel_hi:[1,0]
	v_pk_mul_f32 v[16:17], v[16:17], v[64:65] op_sel_hi:[1,0]

; DI f32x16 mfma32(bf16x8 a, bf16x8 b, f32x16 c) { return __builtin_amdgcn_mfma_f32_32x32x16_bf16(a, b, c, 0, 0, 0); }
; template <int MODE>
; DI void attn_unit(char* lds, const Params& p, int layer, int u) {
;     ...
;     if (t + 1 < NT) { stage(lds + ((t + 1) & 1) * BUFSZ); if (t + 2 < NT) prefetch(t + 2); }
;     const int key0 = (MODE == 3) ? q0 - 64 + 64 * t : 64 * (tlo + t);
;     const bool act = (MODE != 3) || (t >= (wid >> 1) && t <= (wid >> 1) + 2);
;     if (act) {
;       f32x16 S0 = zero16(), S1 = zero16();
;       const char* kb = cur + lr * KST + (MODE == 0 ? comp * 64 : 0) + lh * 16;
; #pragma unroll
;       for (int ks = 0; ks < NKS; ++ks) {
;         const bf16x8 k0 = *(const bf16x8*)(kb + ks * 32), k1 = *(const bf16x8*)(kb + 32 * KST + ks * 32);
;         S0 = mfma32(k0, qf[ks], S0); S1 = mfma32(k1, qf[ks], S1);
;       }
;       float aoff = 0.f;
;       if (MODE == 0) {
;         const float dbase = (float)(key0 + 4 * lh - qrow);
;         if (key0 > qlo + 31) { S0 = S0 - T0; S1 = S1 - T1; aoff = -slope2 * dbase; }
;         else if (key0 + 63 < qlo) { S0 = S0 + T0; S1 = S1 + T1; aoff = slope2 * dbase; }
;         else {
; #pragma unroll
;           for (int r = 0; r < 16; ++r) { const float cc = (float)((r & 3) + 8 * (r >> 2));
;             S0[r] = fmaf(-slope2, fabsf(dbase + cc), S0[r]); S1[r] = fmaf(-slope2, fabsf(dbase + cc + 32.f), S1[r]); }
;         }
;       }
;       if (MODE == 3) {
;         const int rel0 = key0 + 4 * lh - qrow;
; #pragma unroll
;         for (int r = 0; r < 16; ++r) { const int cc = (r & 3) + 8 * (r >> 2);
;           { const int rel = rel0 + cc, v = qrow + rel; const bool ok = (rel >= -64) && (rel <= 64) && (v >= 0) && (v < L); S0[r] = ok ? fmaf(-slope2, fabsf((float)rel), S0[r]) : -1e30f; }
;           { const int rel = rel0 + cc + 32, v = qrow + rel; const bool ok = (rel >= -64) && (rel <= 64) && (v >= 0) && (v < L); S1[r] = ok ? fmaf(-slope2, fabsf((float)rel), S1[r]) : -1e30f; } }
;       }
;       float mx = fmaxf(S0[0], S1[0]);
; #pragma unroll
;       for (int r = 1; r < 16; ++r) mx = max3f(mx, S0[r], S1[r]);
;       mx += aoff;
;       if (__any(mx > m + 8.f)) {
;         mx = fmaxf(mx, __shfl_xor(mx, 32));
;         const float mnew = fmaxf(m, mx);
;         const float al = __builtin_amdgcn_exp2f(m - mnew); l *= al; O0 *= al; O1 *= al;
;         m = mnew;
;       }
.LBB0_600:
	s_or_b64 exec, exec, s[66:67]
	s_cmp_eq_u32 s50, 1
	s_cselect_b32 s50, 0, 0x5800
	v_add3_u32 v32, s51, v123, v108
	s_waitcnt vmcnt(0)
	ds_write_b128 v32, v[92:95] offset:13312
	v_add3_u32 v104, s50, v103, v106
	ds_read_b128 v[32:35], v104
	ds_read_b128 v[88:91], v104 offset:32
	ds_read_b128 v[48:51], v104 offset:6656
	v_readlane_b32 s52, v252, 0
	v_readlane_b32 s60, v252, 8
	v_readlane_b32 s61, v252, 9
	v_readlane_b32 s53, v252, 1
	s_waitcnt lgkmcnt(2)
	v_mfma_f32_32x32x16_bf16 v[32:47], v[32:35], v[84:87], 0
	v_mov_b64_e32 v[92:93], s[60:61]
	v_mad_i64_i32 v[92:93], s[52:53], v116, s72, v[92:93]
	v_ashrrev_i32_e32 v117, 31, v116
	v_lshl_add_u64 v[92:93], v[92:93], 0, v[112:113]
	v_add_co_u32_e32 v92, vcc, s74, v92
	s_waitcnt lgkmcnt(1)
	v_mfma_f32_32x32x16_bf16 v[32:47], v[88:91], v[80:83], v[32:47]
	ds_read_b128 v[88:91], v104 offset:6688
	v_addc_co_u32_e32 v93, vcc, 0, v93, vcc
	v_readlane_b32 s54, v252, 2
	v_readlane_b32 s55, v252, 3
	v_readlane_b32 s56, v252, 4
	v_readlane_b32 s57, v252, 5
	s_waitcnt lgkmcnt(1)
	v_mfma_f32_32x32x16_bf16 v[48:63], v[48:51], v[84:87], 0
	v_readlane_b32 s58, v252, 6
	v_readlane_b32 s59, v252, 7
	v_readlane_b32 s62, v252, 10
	v_readlane_b32 s63, v252, 11
	v_readlane_b32 s64, v252, 12
	v_readlane_b32 s65, v252, 13
	v_readlane_b32 s66, v252, 14
	s_waitcnt lgkmcnt(0)
	v_mfma_f32_32x32x16_bf16 v[48:63], v[88:91], v[80:83], v[48:63]
	ds_read_b128 v[88:91], v104 offset:64
	v_readlane_b32 s67, v252, 15
	s_waitcnt lgkmcnt(0)
	v_mfma_f32_32x32x16_bf16 v[32:47], v[88:91], v[76:79], v[32:47]
	ds_read_b128 v[88:91], v104 offset:6720
	ds_read_b128 v[126:129], v104 offset:96
	s_waitcnt lgkmcnt(1)
	v_mfma_f32_32x32x16_bf16 v[48:63], v[88:91], v[76:79], v[48:63]
	v_lshlrev_b64 v[88:89], 9, v[116:117]
	v_lshl_add_u64 v[88:89], v[110:111], 0, v[88:89]
	global_load_dwordx4 v[88:91], v[88:89], off
	s_nop 0
	global_load_dwordx4 v[96:99], v[92:93], off offset:1280
	s_nop 0
	global_load_dwordx4 v[92:95], v[118:119], off
	s_waitcnt lgkmcnt(0)
	v_mfma_f32_32x32x16_bf16 v[32:47], v[126:129], v[72:75], v[32:47]
	ds_read_b128 v[126:129], v104 offset:6752
	s_waitcnt lgkmcnt(0)
	v_mfma_f32_32x32x16_bf16 v[48:63], v[126:129], v[72:75], v[48:63]
	ds_read_b128 v[126:129], v104 offset:128
	s_waitcnt lgkmcnt(0)
	v_mfma_f32_32x32x16_bf16 v[32:47], v[126:129], v[68:71], v[32:47]
	ds_read_b128 v[126:129], v104 offset:6784
	s_waitcnt lgkmcnt(0)
	v_mfma_f32_32x32x16_bf16 v[48:63], v[126:129], v[68:71], v[48:63]
	ds_read_b128 v[126:129], v104 offset:6816
	s_waitcnt lgkmcnt(0)
	v_mfma_f32_32x32x16_bf16 v[48:63], v[126:129], v[64:67], v[48:63]
	ds_read_b128 v[126:129], v104 offset:160
	s_waitcnt lgkmcnt(0)
	v_mfma_f32_32x32x16_bf16 v[32:47], v[126:129], v[64:67], v[32:47]
	s_nop 8
	v_max_f32_e32 v104, v48, v48
	s_nop 1
	v_max_f32_e32 v105, v32, v32
	v_max_f32_e32 v104, v105, v104
	v_max3_f32 v104, v104, v33, v49
	v_add_f32_e32 v105, 0x41000000, v107
	v_max_f32_e32 v246, v34, v50
	v_max3_f32 v104, v104, v35, v51
	v_max3_f32 v246, v246, v36, v52
	v_max3_f32 v104, v104, v37, v53
	v_max3_f32 v246, v246, v38, v54
	v_max3_f32 v104, v104, v39, v55
	v_max3_f32 v246, v246, v40, v56
	v_max3_f32 v104, v104, v41, v57
	v_max3_f32 v246, v246, v42, v58
	v_max3_f32 v104, v104, v43, v59
	v_max3_f32 v246, v246, v44, v60
	v_max3_f32 v104, v104, v45, v61
	v_max3_f32 v246, v246, v46, v62
	v_max3_f32 v104, v104, v47, v63
	v_max_f32_e32 v104, v104, v246
	v_cmp_gt_f32_e32 vcc, v104, v105
	s_cbranch_vccz .LBB0_597
	v_cmp_lt_i32_e32 vcc, v209, v208
	v_add_f32_e32 v104, 0, v104
	s_nop 0
	v_cndmask_b32_e32 v105, v207, v209, vcc
	v_lshlrev_b32_e32 v105, 2, v105
	ds_bpermute_b32 v105, v105, v104
	s_waitcnt lgkmcnt(0)
	v_max3_f32 v105, v107, v104, v105
	v_sub_f32_e32 v104, v107, v105
	v_exp_f32_e32 v104, v104
	v_mov_b32_e32 v107, v105
	v_mul_f32_e32 v109, v109, v104
	v_pk_mul_f32 v[14:15], v[14:15], v[104:105] op_sel_hi:[1,0]
	v_pk_mul_f32 v[12:13], v[12:13], v[104:105] op_sel_hi:[1,0]
	v_pk_mul_f32 v[10:11], v[10:11], v[104:105] op_sel_hi:[1,0]
	v_pk_mul_f32 v[8:9], v[8:9], v[104:105] op_sel_hi:[1,0]
	v_pk_mul_f32 v[6:7], v[6:7], v[104:105] op_sel_hi:[1,0]
	v_pk_mul_f32 v[4:5], v[4:5], v[104:105] op_sel_hi:[1,0]
	v_pk_mul_f32 v[2:3], v[2:3], v[104:105] op_sel_hi:[1,0]
	v_pk_mul_f32 v[0:1], v[0:1], v[104:105] op_sel_hi:[1,0]
	v_pk_mul_f32 v[30:31], v[30:31], v[104:105] op_sel_hi:[1,0]
	v_pk_mul_f32 v[28:29], v[28:29], v[104:105] op_sel_hi:[1,0]
	v_pk_mul_f32 v[26:27], v[26:27], v[104:105] op_sel_hi:[1,0]
	v_pk_mul_f32 v[24:25], v[24:25], v[104:105] op_sel_hi:[1,0]
	v_pk_mul_f32 v[22:23], v[22:23], v[104:105] op_sel_hi:[1,0]
	v_pk_mul_f32 v[20:21], v[20:21], v[104:105] op_sel_hi:[1,0]
	v_pk_mul_f32 v[18:19], v[18:19], v[104:105] op_sel_hi:[1,0]
	v_pk_mul_f32 v[16:17], v[16:17], v[104:105] op_sel_hi:[1,0]
	s_branch .LBB0_597

; DI float max3f(float a, float b, float c) { float d; asm("v_max3_f32 %0, %1, %2, %3" : "=v"(d) : "v"(a), "v"(b), "v"(c)); return d; }
; template <int MODE>
; DI void attn_unit(char* lds, const Params& p, int layer, int u) {
;     ...
;       float mx = fmaxf(S0[0], S1[0]);
; #pragma unroll
;       for (int r = 1; r < 16; ++r) mx = max3f(mx, S0[r], S1[r]);
;       mx += aoff;
;       if (__any(mx > m + 8.f)) {
;         mx = fmaxf(mx, __shfl_xor(mx, 32));
;         const float mnew = fmaxf(m, mx);
;         const float al = __builtin_amdgcn_exp2f(m - mnew); l *= al; O0 *= al; O1 *= al;
;         m = mnew;
;       }
.LBB0_632:
	s_or_b64 exec, exec, s[68:69]
	s_nop 3
	v_max_f32_e32 v64, v48, v48
	v_max_f32_e32 v65, v32, v32
	v_max_f32_e32 v64, v65, v64
	v_max3_f32 v64, v64, v33, v49
	v_max_f32_e32 v246, v34, v50
	v_max3_f32 v64, v64, v35, v51
	v_max3_f32 v246, v246, v36, v52
	v_max3_f32 v64, v64, v37, v53
	v_max3_f32 v246, v246, v38, v54
	v_max3_f32 v64, v64, v39, v55
	v_max3_f32 v246, v246, v40, v56
	v_max3_f32 v64, v64, v41, v57
	v_max3_f32 v246, v246, v42, v58
	v_max3_f32 v64, v64, v43, v59
	v_max3_f32 v246, v246, v44, v60
	v_max3_f32 v64, v64, v45, v61
	v_max3_f32 v246, v246, v46, v62
	v_max_f32_e32 v64, v64, v246
	v_max3_f32 v114, v64, v47, v63
	v_pk_add_f32 v[64:65], v[162:163], v[114:115]
	s_nop 0
	v_cmp_gt_f32_e32 vcc, v64, v65
	s_cbranch_vccz .LBB0_634
	v_cmp_lt_i32_e32 vcc, v209, v208
	s_nop 1
	v_cndmask_b32_e32 v65, v207, v209, vcc
	v_lshlrev_b32_e32 v65, 2, v65
	ds_bpermute_b32 v65, v65, v64
	s_waitcnt lgkmcnt(0)
	v_max3_f32 v65, v163, v64, v65
	v_sub_f32_e32 v64, v163, v65
	v_exp_f32_e32 v64, v64
	v_mov_b32_e32 v163, v65
	v_mul_f32_e32 v121, v121, v64
	v_pk_mul_f32 v[14:15], v[14:15], v[64:65] op_sel_hi:[1,0]
	v_pk_mul_f32 v[12:13], v[12:13], v[64:65] op_sel_hi:[1,0]
	v_pk_mul_f32 v[10:11], v[10:11], v[64:65] op_sel_hi:[1,0]
	v_pk_mul_f32 v[8:9], v[8:9], v[64:65] op_sel_hi:[1,0]
	v_pk_mul_f32 v[6:7], v[6:7], v[64:65] op_sel_hi:[1,0]
	v_pk_mul_f32 v[4:5], v[4:5], v[64:65] op_sel_hi:[1,0]
	v_pk_mul_f32 v[2:3], v[2:3], v[64:65] op_sel_hi:[1,0]
	v_pk_mul_f32 v[0:1], v[0:1], v[64:65] op_sel_hi:[1,0]
	v_pk_mul_f32 v[30:31], v[30:31], v[64:65] op_sel_hi:[1,0]
	v_pk_mul_f32 v[28:29], v[28:29], v[64:65] op_sel_hi:[1,0]
	v_pk_mul_f32 v[26:27], v[26:27], v[64:65] op_sel_hi:[1,0]
	v_pk_mul_f32 v[24:25], v[24:25], v[64:65] op_sel_hi:[1,0]
	v_pk_mul_f32 v[22:23], v[22:23], v[64:65] op_sel_hi:[1,0]
	v_pk_mul_f32 v[20:21], v[20:21], v[64:65] op_sel_hi:[1,0]
	v_pk_mul_f32 v[18:19], v[18:19], v[64:65] op_sel_hi:[1,0]
	v_pk_mul_f32 v[16:17], v[16:17], v[64:65] op_sel_hi:[1,0]

; template <int MODE>
; DI void attn_unit(char* lds, const Params& p, int layer, int u) {
;     ...
;       f32x16 S0 = zero16(), S1 = zero16();
;       const char* kb = cur + lr * KST + (MODE == 0 ? comp * 64 : 0) + lh * 16;
; #pragma unroll
;       for (int ks = 0; ks < NKS; ++ks) {
;         const bf16x8 k0 = *(const bf16x8*)(kb + ks * 32), k1 = *(const bf16x8*)(kb + 32 * KST + ks * 32);
;         S0 = mfma32(k0, qf[ks], S0); S1 = mfma32(k1, qf[ks], S1);
;       }
;       float aoff = 0.f;
;       if (MODE == 0) {
;         const float dbase = (float)(key0 + 4 * lh - qrow);
;         if (key0 > qlo + 31) { S0 = S0 - T0; S1 = S1 - T1; aoff = -slope2 * dbase; }
;         else if (key0 + 63 < qlo) { S0 = S0 + T0; S1 = S1 + T1; aoff = slope2 * dbase; }
;         else {
; #pragma unroll
;           for (int r = 0; r < 16; ++r) { const float cc = (float)((r & 3) + 8 * (r >> 2));
;             S0[r] = fmaf(-slope2, fabsf(dbase + cc), S0[r]); S1[r] = fmaf(-slope2, fabsf(dbase + cc + 32.f), S1[r]); }
;         }
;       }
;       if (MODE == 3) {
;         const int rel0 = key0 + 4 * lh - qrow;
; #pragma unroll
;         for (int r = 0; r < 16; ++r) { const int cc = (r & 3) + 8 * (r >> 2);
;           { const int rel = rel0 + cc, v = qrow + rel; const bool ok = (rel >= -64) && (rel <= 64) && (v >= 0) && (v < L); S0[r] = ok ? fmaf(-slope2, fabsf((float)rel), S0[r]) : -1e30f; }
;           { const int rel = rel0 + cc + 32, v = qrow + rel; const bool ok = (rel >= -64) && (rel <= 64) && (v >= 0) && (v < L); S1[r] = ok ? fmaf(-slope2, fabsf((float)rel), S1[r]) : -1e30f; } }
;       }
;       float mx = fmaxf(S0[0], S1[0]);
; #pragma unroll
;       for (int r = 1; r < 16; ++r) mx = max3f(mx, S0[r], S1[r]);
;       mx += aoff;
;       if (__any(mx > m + 8.f)) {
;         mx = fmaxf(mx, __shfl_xor(mx, 32));
;         const float mnew = fmaxf(m, mx);
;         const float al = __builtin_amdgcn_exp2f(m - mnew); l *= al; O0 *= al; O1 *= al;
;         m = mnew;
;       }
;       { const f32x2 nm = {aoff - m, aoff - m};
; #pragma unroll
;         for (int r = 0; r < 8; ++r) {
;           f32x2 a = {S0[2 * r], S0[2 * r + 1]}, b = {S1[2 * r], S1[2 * r + 1]};
;           asm("v_pk_add_f32 %0, %1, %2" : "=v"(a) : "v"(a), "v"(nm));
;           asm("v_pk_add_f32 %0, %1, %2" : "=v"(b) : "v"(b), "v"(nm));
.LBB0_646:
	s_or_b64 exec, exec, s[66:67]
	s_waitcnt vmcnt(0)
	ds_write_b128 v122, v[92:95] offset:35840
	v_add_u32_e32 v94, v103, v106
	ds_read_b128 v[32:35], v94
	ds_read_b128 v[88:91], v94 offset:32
	ds_read_b128 v[48:51], v94 offset:6656
	v_add_f32_e32 v93, 0x41000000, v107
	s_waitcnt lgkmcnt(2)
	v_mfma_f32_32x32x16_bf16 v[32:47], v[32:35], v[84:87], 0
	s_waitcnt lgkmcnt(1)
	v_mfma_f32_32x32x16_bf16 v[32:47], v[88:91], v[80:83], v[32:47]
	ds_read_b128 v[88:91], v94 offset:6688
	s_waitcnt lgkmcnt(1)
	v_mfma_f32_32x32x16_bf16 v[48:63], v[48:51], v[84:87], 0
	s_waitcnt lgkmcnt(0)
	v_mfma_f32_32x32x16_bf16 v[48:63], v[88:91], v[80:83], v[48:63]
	ds_read_b128 v[88:91], v94 offset:64
	s_waitcnt lgkmcnt(0)
	v_mfma_f32_32x32x16_bf16 v[32:47], v[88:91], v[76:79], v[32:47]
	ds_read_b128 v[88:91], v94 offset:6720
	s_waitcnt lgkmcnt(0)
	v_mfma_f32_32x32x16_bf16 v[48:63], v[88:91], v[76:79], v[48:63]
	ds_read_b128 v[88:91], v94 offset:96
	s_waitcnt lgkmcnt(0)
	v_mfma_f32_32x32x16_bf16 v[32:47], v[88:91], v[72:75], v[32:47]
	ds_read_b128 v[88:91], v94 offset:6752
	s_waitcnt lgkmcnt(0)
	v_mfma_f32_32x32x16_bf16 v[48:63], v[88:91], v[72:75], v[48:63]
	ds_read_b128 v[88:91], v94 offset:128
	s_waitcnt lgkmcnt(0)
	v_mfma_f32_32x32x16_bf16 v[32:47], v[88:91], v[68:71], v[32:47]
	ds_read_b128 v[88:91], v94 offset:6784
	s_waitcnt lgkmcnt(0)
	v_mfma_f32_32x32x16_bf16 v[48:63], v[88:91], v[68:71], v[48:63]
	ds_read_b128 v[88:91], v94 offset:6816
	s_waitcnt lgkmcnt(0)
	v_mfma_f32_32x32x16_bf16 v[48:63], v[88:91], v[64:67], v[48:63]
	ds_read_b128 v[88:91], v94 offset:160
	s_waitcnt lgkmcnt(0)
	v_mfma_f32_32x32x16_bf16 v[32:47], v[88:91], v[64:67], v[32:47]
	s_nop 8
	v_max_f32_e32 v92, v48, v48
	s_nop 1
	v_max_f32_e32 v88, v32, v32
	v_max_f32_e32 v88, v88, v92
	v_max3_f32 v88, v88, v33, v49
	v_max_f32_e32 v246, v34, v50
	v_max3_f32 v88, v88, v35, v51
	v_max3_f32 v246, v246, v36, v52
	v_max3_f32 v88, v88, v37, v53
	v_max3_f32 v246, v246, v38, v54
	v_max3_f32 v88, v88, v39, v55
	v_max3_f32 v246, v246, v40, v56
	v_max3_f32 v88, v88, v41, v57
	v_max3_f32 v246, v246, v42, v58
	v_max3_f32 v88, v88, v43, v59
	v_max3_f32 v246, v246, v44, v60
	v_max3_f32 v88, v88, v45, v61
	v_max3_f32 v246, v246, v46, v62
	v_max3_f32 v88, v88, v47, v63
	v_max_f32_e32 v88, v88, v246
	v_cmp_gt_f32_e32 vcc, v88, v93
	s_cbranch_vccz .LBB0_648
	v_cmp_lt_i32_e32 vcc, v209, v208
	v_add_f32_e32 v88, 0, v88
	s_nop 0
	v_cndmask_b32_e32 v89, v207, v209, vcc
	v_lshlrev_b32_e32 v89, 2, v89
	ds_bpermute_b32 v89, v89, v88
	s_waitcnt lgkmcnt(0)
	v_max3_f32 v89, v107, v88, v89
	v_sub_f32_e32 v88, v107, v89
	v_exp_f32_e32 v88, v88
	v_sub_f32_e32 v104, 0, v89
	v_add_f32_e32 v93, 0x41000000, v89
	v_mov_b32_e32 v107, v89
	v_mul_f32_e32 v109, v109, v88
	v_pk_mul_f32 v[14:15], v[14:15], v[88:89] op_sel_hi:[1,0]
	v_pk_mul_f32 v[12:13], v[12:13], v[88:89] op_sel_hi:[1,0]
	v_pk_mul_f32 v[10:11], v[10:11], v[88:89] op_sel_hi:[1,0]
	v_pk_mul_f32 v[8:9], v[8:9], v[88:89] op_sel_hi:[1,0]
	v_pk_mul_f32 v[6:7], v[6:7], v[88:89] op_sel_hi:[1,0]
	v_pk_mul_f32 v[4:5], v[4:5], v[88:89] op_sel_hi:[1,0]
	v_pk_mul_f32 v[2:3], v[2:3], v[88:89] op_sel_hi:[1,0]
	v_pk_mul_f32 v[0:1], v[0:1], v[88:89] op_sel_hi:[1,0]
	v_pk_mul_f32 v[30:31], v[30:31], v[88:89] op_sel_hi:[1,0]
	v_pk_mul_f32 v[28:29], v[28:29], v[88:89] op_sel_hi:[1,0]
	v_pk_mul_f32 v[26:27], v[26:27], v[88:89] op_sel_hi:[1,0]
	v_pk_mul_f32 v[24:25], v[24:25], v[88:89] op_sel_hi:[1,0]
	v_pk_mul_f32 v[22:23], v[22:23], v[88:89] op_sel_hi:[1,0]
	v_pk_mul_f32 v[20:21], v[20:21], v[88:89] op_sel_hi:[1,0]
	v_pk_mul_f32 v[18:19], v[18:19], v[88:89] op_sel_hi:[1,0]
	v_pk_mul_f32 v[16:17], v[16:17], v[88:89] op_sel_hi:[1,0]
.LBB0_648:
	v_mov_b32_e32 v105, v104
	v_pk_add_f32 v[32:33], v[32:33], v[104:105]
	v_pk_add_f32 v[48:49], v[48:49], v[104:105]
	v_pk_add_f32 v[34:35], v[34:35], v[104:105]
	v_pk_add_f32 v[50:51], v[50:51], v[104:105]
	v_pk_add_f32 v[36:37], v[36:37], v[104:105]
	v_pk_add_f32 v[52:53], v[52:53], v[104:105]
	s_nop 0
	v_exp_f32_e32 v32, v32
	v_exp_f32_e32 v88, v48
	v_exp_f32_e32 v33, v33
	v_exp_f32_e32 v89, v49
	v_exp_f32_e32 v34, v34
	v_exp_f32_e32 v50, v50
	v_exp_f32_e32 v35, v35
	v_exp_f32_e32 v51, v51
	v_exp_f32_e32 v36, v36
	v_exp_f32_e32 v52, v52
	v_exp_f32_e32 v37, v37
	v_exp_f32_e32 v53, v53
	v_pk_add_f32 v[120:121], v[32:33], v[88:89]
	v_pk_add_f32 v[38:39], v[38:39], v[104:105]
	v_pk_add_f32 v[54:55], v[54:55], v[104:105]
	v_pk_add_f32 v[118:119], v[34:35], v[50:51]
	v_add_f32_e32 v92, 0, v120
	v_exp_f32_e32 v38, v38
	v_exp_f32_e32 v54, v54
	v_exp_f32_e32 v39, v39
	v_exp_f32_e32 v55, v55
	v_add_f32_e32 v92, v121, v92
	v_pk_add_f32 v[40:41], v[40:41], v[104:105]
	v_pk_add_f32 v[56:57], v[56:57], v[104:105]
	v_add_f32_e32 v92, v118, v92
	v_exp_f32_e32 v40, v40
	v_exp_f32_e32 v56, v56
	v_exp_f32_e32 v41, v41
	v_exp_f32_e32 v57, v57
	v_pk_add_f32 v[116:117], v[36:37], v[52:53]
	v_add_f32_e32 v92, v119, v92
	v_pk_add_f32 v[42:43], v[42:43], v[104:105]
	v_pk_add_f32 v[58:59], v[58:59], v[104:105]
	v_add_f32_e32 v92, v116, v92
	v_exp_f32_e32 v42, v42
	v_exp_f32_e32 v58, v58
	v_exp_f32_e32 v43, v43
	v_exp_f32_e32 v59, v59
	v_pk_add_f32 v[110:111], v[38:39], v[54:55]
	v_add_f32_e32 v92, v117, v92
	v_pk_add_f32 v[60:61], v[60:61], v[104:105]
	v_add_f32_e32 v92, v110, v92
	v_pk_add_f32 v[44:45], v[44:45], v[104:105]
	v_exp_f32_e32 v60, v60
	v_exp_f32_e32 v90, v44
	v_exp_f32_e32 v91, v45
	v_exp_f32_e32 v61, v61
	v_pk_add_f32 v[98:99], v[40:41], v[56:57]
	v_add_f32_e32 v92, v111, v92
	v_pk_add_f32 v[62:63], v[62:63], v[104:105]
	v_add_f32_e32 v92, v98, v92
	v_pk_add_f32 v[46:47], v[46:47], v[104:105]
	v_exp_f32_e32 v62, v62
	v_exp_f32_e32 v96, v46
	v_exp_f32_e32 v97, v47
	v_exp_f32_e32 v63, v63
	v_pk_add_f32 v[48:49], v[42:43], v[58:59]
	v_add_f32_e32 v92, v99, v92
	v_add_f32_e32 v48, v48, v92
	v_pk_add_f32 v[46:47], v[90:91], v[60:61]
	v_add_f32_e32 v48, v49, v48
	v_add_f32_e32 v46, v46, v48
	v_lshlrev_b32_e32 v95, 6, v114
	v_pk_add_f32 v[44:45], v[96:97], v[62:63]
	v_add_f32_e32 v46, v47, v46
	v_sub_u32_e32 v49, v103, v95
	v_add_f32_e32 v44, v44, v46
	v_add_u32_e32 v49, v49, v102
	v_add_f32_e32 v48, v45, v44
	v_cvt_pk_bf16_f32 v44, v32, v33
	v_cvt_pk_bf16_f32 v33, v58, v59
	v_add_u32_e32 v58, 0x3000, v49
	v_cvt_pk_bf16_f32 v46, v36, v37
	v_cvt_pk_bf16_f32 v47, v38, v39
	v_cvt_pk_bf16_f32 v37, v50, v51
	v_cvt_pk_bf16_f32 v38, v52, v53
	v_cvt_pk_bf16_f32 v39, v54, v55
	v_cvt_pk_bf16_f32 v32, v56, v57
	ds_read2_b64 v[50:53], v58 offset0:128 offset1:130
	ds_read2_b64 v[54:57], v58 offset0:132 offset1:134
	v_cvt_pk_bf16_f32 v45, v34, v35
	v_add_u32_e32 v49, 0x4000, v49
	v_cvt_pk_bf16_f32 v40, v40, v41
	s_waitcnt lgkmcnt(1)
; template <int MODE>
; DI void attn_unit(char* lds, const Params& p, int layer, int u) {
;     ...
;       f32x16 S0 = zero16(), S1 = zero16();
;       const char* kb = cur + lr * KST + (MODE == 0 ? comp * 64 : 0) + lh * 16;
; #pragma unroll
;       for (int ks = 0; ks < NKS; ++ks) {
;         const bf16x8 k0 = *(const bf16x8*)(kb + ks * 32), k1 = *(const bf16x8*)(kb + 32 * KST + ks * 32);
;         S0 = mfma32(k0, qf[ks], S0); S1 = mfma32(k1, qf[ks], S1);
;       }
;       float aoff = 0.f;
;       if (MODE == 0) {
;         const float dbase = (float)(key0 + 4 * lh - qrow);
;         if (key0 > qlo + 31) { S0 = S0 - T0; S1 = S1 - T1; aoff = -slope2 * dbase; }
;         else if (key0 + 63 < qlo) { S0 = S0 + T0; S1 = S1 + T1; aoff = slope2 * dbase; }
;         else {
; #pragma unroll
;           for (int r = 0; r < 16; ++r) { const float cc = (float)((r & 3) + 8 * (r >> 2));
;             S0[r] = fmaf(-slope2, fabsf(dbase + cc), S0[r]); S1[r] = fmaf(-slope2, fabsf(dbase + cc + 32.f), S1[r]); }
;         }
;       }
;       if (MODE == 3) {
;         const int rel0 = key0 + 4 * lh - qrow;
; #pragma unroll
;         for (int r = 0; r < 16; ++r) { const int cc = (r & 3) + 8 * (r >> 2);
;           { const int rel = rel0 + cc, v = qrow + rel; const bool ok = (rel >= -64) && (rel <= 64) && (v >= 0) && (v < L); S0[r] = ok ? fmaf(-slope2, fabsf((float)rel), S0[r]) : -1e30f; }
;           { const int rel = rel0 + cc + 32, v = qrow + rel; const bool ok = (rel >= -64) && (rel <= 64) && (v >= 0) && (v < L); S1[r] = ok ? fmaf(-slope2, fabsf((float)rel), S1[r]) : -1e30f; } }
;       }
;       float mx = fmaxf(S0[0], S1[0]);
; #pragma unroll
;       for (int r = 1; r < 16; ++r) mx = max3f(mx, S0[r], S1[r]);
;       mx += aoff;
;       if (__any(mx > m + 8.f)) {
;         mx = fmaxf(mx, __shfl_xor(mx, 32));
;     ...
;       const char* vb = cur + VOFF + lr * VST + lh * 8;
; #pragma unroll
;       for (int s = 0; s < 4; ++s) {
;         { const s16x4 lo = *(const s16x4*)(vb + s * 32), hi = *(const s16x4*)(vb + s * 32 + 16);
;           O0 = mfma32(__builtin_shufflevector(lo, hi, 0, 1, 2, 3, 4, 5, 6, 7), pf[s], O0); }
;         { const s16x4 lo = *(const s16x4*)(vb + 32 * VST + s * 32), hi = *(const s16x4*)(vb + 32 * VST + s * 32 + 16);
;           O1 = mfma32(__builtin_shufflevector(lo, hi, 0, 1, 2, 3, 4, 5, 6, 7), pf[s], O1); }
;       }
;     }
;     __syncthreads();
	v_mfma_f32_32x32x16_bf16 v[0:15], v[50:53], v[44:47], v[0:15]
	ds_read2_b64 v[50:53], v49 offset0:192 offset1:194
	v_cvt_pk_bf16_f32 v41, v42, v43
	v_cvt_pk_bf16_f32 v42, v90, v91
	v_cvt_pk_bf16_f32 v43, v96, v97
	v_cvt_pk_bf16_f32 v36, v88, v89
	v_cvt_pk_bf16_f32 v34, v60, v61
	v_cvt_pk_bf16_f32 v35, v62, v63
	s_waitcnt lgkmcnt(0)
	v_mfma_f32_32x32x16_bf16 v[16:31], v[50:53], v[44:47], v[16:31]
	ds_read2_b64 v[44:47], v49 offset0:196 offset1:198
	v_add_f32_e32 v92, v109, v48
	v_mfma_f32_32x32x16_bf16 v[0:15], v[54:57], v[40:43], v[0:15]
	s_waitcnt lgkmcnt(0)
	v_mfma_f32_32x32x16_bf16 v[16:31], v[44:47], v[40:43], v[16:31]
	ds_read2_b64 v[40:43], v58 offset0:136 offset1:138
	s_waitcnt lgkmcnt(0)
	v_mfma_f32_32x32x16_bf16 v[0:15], v[40:43], v[36:39], v[0:15]
	ds_read2_b64 v[40:43], v49 offset0:200 offset1:202
	s_waitcnt lgkmcnt(0)
	v_mfma_f32_32x32x16_bf16 v[16:31], v[40:43], v[36:39], v[16:31]
	ds_read2_b64 v[36:39], v58 offset0:140 offset1:142
	s_waitcnt lgkmcnt(0)
	v_mfma_f32_32x32x16_bf16 v[0:15], v[36:39], v[32:35], v[0:15]
	ds_read2_b64 v[36:39], v49 offset0:204 offset1:206
	s_waitcnt lgkmcnt(0)
	s_barrier
	v_mfma_f32_32x32x16_bf16 v[16:31], v[36:39], v[32:35], v[16:31]
	ds_read_b128 v[88:91], v94 offset:29344
	ds_read_b128 v[96:99], v94 offset:22688
	ds_read_b128 v[108:111], v94 offset:29312
	ds_read_b128 v[116:119], v94 offset:22656
	ds_read_b128 v[120:123], v94 offset:29280
	ds_read_b128 v[124:127], v94 offset:22624
	ds_read_b128 v[128:131], v94 offset:29248
	ds_read_b128 v[132:135], v94 offset:22592
	ds_read_b128 v[136:139], v94 offset:29216
	ds_read_b128 v[32:35], v94 offset:22528
	ds_read_b128 v[140:143], v94 offset:22560
	ds_read_b128 v[48:51], v94 offset:29184
	s_waitcnt lgkmcnt(2)
	v_mfma_f32_32x32x16_bf16 v[32:47], v[32:35], v[84:87], 0
	s_waitcnt lgkmcnt(0)
	v_mfma_f32_32x32x16_bf16 v[48:63], v[48:51], v[84:87], 0
	v_mfma_f32_32x32x16_bf16 v[32:47], v[140:143], v[80:83], v[32:47]
	v_mfma_f32_32x32x16_bf16 v[48:63], v[136:139], v[80:83], v[48:63]
	v_mfma_f32_32x32x16_bf16 v[32:47], v[132:135], v[76:79], v[32:47]
	v_mfma_f32_32x32x16_bf16 v[48:63], v[128:131], v[76:79], v[48:63]
	v_mfma_f32_32x32x16_bf16 v[32:47], v[124:127], v[72:75], v[32:47]
	v_mfma_f32_32x32x16_bf16 v[48:63], v[120:123], v[72:75], v[48:63]
	v_mfma_f32_32x32x16_bf16 v[32:47], v[116:119], v[68:71], v[32:47]
	v_mfma_f32_32x32x16_bf16 v[48:63], v[108:111], v[68:71], v[48:63]
	v_mfma_f32_32x32x16_bf16 v[32:47], v[96:99], v[64:67], v[32:47]
	v_mfma_f32_32x32x16_bf16 v[48:63], v[88:91], v[64:67], v[48:63]
	s_nop 10
	v_max_f32_e32 v65, v32, v32
	v_max_f32_e32 v64, v48, v48
	v_max_f32_e32 v64, v65, v64
	v_max3_f32 v64, v64, v33, v49
	v_max_f32_e32 v246, v34, v50
	v_max3_f32 v64, v64, v35, v51
	v_max3_f32 v246, v246, v36, v52
	v_max3_f32 v64, v64, v37, v53
	v_max3_f32 v246, v246, v38, v54
	v_max3_f32 v64, v64, v39, v55
	v_max3_f32 v246, v246, v40, v56
	v_max3_f32 v64, v64, v41, v57
	v_max3_f32 v246, v246, v42, v58
	v_max3_f32 v64, v64, v43, v59
	v_max3_f32 v246, v246, v44, v60
	v_max3_f32 v64, v64, v45, v61
	v_max3_f32 v246, v246, v46, v62
	v_max3_f32 v64, v64, v47, v63
	v_max_f32_e32 v64, v64, v246
	v_cmp_gt_f32_e32 vcc, v64, v93
	s_cbranch_vccz .LBB0_650
	v_cmp_lt_i32_e32 vcc, v209, v208
	v_add_f32_e32 v64, 0, v64
	s_nop 0
	v_cndmask_b32_e32 v65, v207, v209, vcc
	v_lshlrev_b32_e32 v65, 2, v65
	ds_bpermute_b32 v65, v65, v64
	s_waitcnt lgkmcnt(0)
	v_max3_f32 v65, v107, v64, v65
	v_sub_f32_e32 v64, v107, v65
	v_exp_f32_e32 v64, v64
	v_sub_f32_e32 v104, 0, v65
	v_mov_b32_e32 v105, v104
	v_mul_f32_e32 v92, v92, v64
	v_pk_mul_f32 v[14:15], v[14:15], v[64:65] op_sel_hi:[1,0]
	v_pk_mul_f32 v[12:13], v[12:13], v[64:65] op_sel_hi:[1,0]
	v_pk_mul_f32 v[10:11], v[10:11], v[64:65] op_sel_hi:[1,0]
	v_pk_mul_f32 v[8:9], v[8:9], v[64:65] op_sel_hi:[1,0]
	v_pk_mul_f32 v[6:7], v[6:7], v[64:65] op_sel_hi:[1,0]
	v_pk_mul_f32 v[4:5], v[4:5], v[64:65] op_sel_hi:[1,0]
	v_pk_mul_f32 v[2:3], v[2:3], v[64:65] op_sel_hi:[1,0]
	v_pk_mul_f32 v[0:1], v[0:1], v[64:65] op_sel_hi:[1,0]
	v_pk_mul_f32 v[30:31], v[30:31], v[64:65] op_sel_hi:[1,0]
	v_pk_mul_f32 v[28:29], v[28:29], v[64:65] op_sel_hi:[1,0]
	v_pk_mul_f32 v[26:27], v[26:27], v[64:65] op_sel_hi:[1,0]
	v_pk_mul_f32 v[24:25], v[24:25], v[64:65] op_sel_hi:[1,0]
	v_pk_mul_f32 v[22:23], v[22:23], v[64:65] op_sel_hi:[1,0]
	v_pk_mul_f32 v[20:21], v[20:21], v[64:65] op_sel_hi:[1,0]
	v_pk_mul_f32 v[18:19], v[18:19], v[64:65] op_sel_hi:[1,0]
	v_pk_mul_f32 v[16:17], v[16:17], v[64:65] op_sel_hi:[1,0]

; DI f32x16 mfma32(bf16x8 a, bf16x8 b, f32x16 c) { return __builtin_amdgcn_mfma_f32_32x32x16_bf16(a, b, c, 0, 0, 0); }
; template <int MODE>
; DI void attn_unit(char* lds, const Params& p, int layer, int u) {
;     ...
;     if (t + 1 < NT) { stage(lds + ((t + 1) & 1) * BUFSZ); if (t + 2 < NT) prefetch(t + 2); }
;     const int key0 = (MODE == 3) ? q0 - 64 + 64 * t : 64 * (tlo + t);
;     const bool act = (MODE != 3) || (t >= (wid >> 1) && t <= (wid >> 1) + 2);
;     if (act) {
;       f32x16 S0 = zero16(), S1 = zero16();
;       const char* kb = cur + lr * KST + (MODE == 0 ? comp * 64 : 0) + lh * 16;
; #pragma unroll
;       for (int ks = 0; ks < NKS; ++ks) {
;         const bf16x8 k0 = *(const bf16x8*)(kb + ks * 32), k1 = *(const bf16x8*)(kb + 32 * KST + ks * 32);
;         S0 = mfma32(k0, qf[ks], S0); S1 = mfma32(k1, qf[ks], S1);
;       }
;       float aoff = 0.f;
;       if (MODE == 0) {
;         const float dbase = (float)(key0 + 4 * lh - qrow);
;         if (key0 > qlo + 31) { S0 = S0 - T0; S1 = S1 - T1; aoff = -slope2 * dbase; }
;         else if (key0 + 63 < qlo) { S0 = S0 + T0; S1 = S1 + T1; aoff = slope2 * dbase; }
;         else {
; #pragma unroll
;           for (int r = 0; r < 16; ++r) { const float cc = (float)((r & 3) + 8 * (r >> 2));
;             S0[r] = fmaf(-slope2, fabsf(dbase + cc), S0[r]); S1[r] = fmaf(-slope2, fabsf(dbase + cc + 32.f), S1[r]); }
;         }
;       }
;       if (MODE == 3) {
;         const int rel0 = key0 + 4 * lh - qrow;
; #pragma unroll
;         for (int r = 0; r < 16; ++r) { const int cc = (r & 3) + 8 * (r >> 2);
;           { const int rel = rel0 + cc, v = qrow + rel; const bool ok = (rel >= -64) && (rel <= 64) && (v >= 0) && (v < L); S0[r] = ok ? fmaf(-slope2, fabsf((float)rel), S0[r]) : -1e30f; }
;           { const int rel = rel0 + cc + 32, v = qrow + rel; const bool ok = (rel >= -64) && (rel <= 64) && (v >= 0) && (v < L); S1[r] = ok ? fmaf(-slope2, fabsf((float)rel), S1[r]) : -1e30f; } }
;       }
;       float mx = fmaxf(S0[0], S1[0]);
; #pragma unroll
;       for (int r = 1; r < 16; ++r) mx = max3f(mx, S0[r], S1[r]);
;       mx += aoff;
;       if (__any(mx > m + 8.f)) {
;         mx = fmaxf(mx, __shfl_xor(mx, 32));
;         const float mnew = fmaxf(m, mx);
;         const float al = __builtin_amdgcn_exp2f(m - mnew); l *= al; O0 *= al; O1 *= al;
;         m = mnew;
;       }
.LBB0_1577:
	s_or_b64 exec, exec, s[66:67]
	s_cmp_eq_u32 s50, 1
	s_cselect_b32 s50, 0, 0x5800
	v_add3_u32 v32, s51, v123, v108
	s_waitcnt vmcnt(0)
	ds_write_b128 v32, v[92:95] offset:13312
	v_add3_u32 v104, s50, v103, v106
	ds_read_b128 v[32:35], v104
	ds_read_b128 v[88:91], v104 offset:32
	ds_read_b128 v[48:51], v104 offset:6656
	v_readlane_b32 s8, v252, 0
	v_readlane_b32 s16, v252, 8
	v_readlane_b32 s17, v252, 9
	v_ashrrev_i32_e32 v117, 31, v116
	s_waitcnt lgkmcnt(2)
	v_mfma_f32_32x32x16_bf16 v[32:47], v[32:35], v[84:87], 0
	v_mov_b64_e32 v[92:93], s[16:17]
	v_mad_i64_i32 v[92:93], s[52:53], v116, s72, v[92:93]
	v_lshl_add_u64 v[92:93], v[92:93], 0, v[112:113]
	v_add_co_u32_e32 v92, vcc, s74, v92
	v_readlane_b32 s9, v252, 1
	s_waitcnt lgkmcnt(1)
	v_mfma_f32_32x32x16_bf16 v[32:47], v[88:91], v[80:83], v[32:47]
	ds_read_b128 v[88:91], v104 offset:6688
	v_addc_co_u32_e32 v93, vcc, 0, v93, vcc
	v_readlane_b32 s10, v252, 2
	v_readlane_b32 s11, v252, 3
	v_readlane_b32 s12, v252, 4
	v_readlane_b32 s13, v252, 5
	s_waitcnt lgkmcnt(1)
	v_mfma_f32_32x32x16_bf16 v[48:63], v[48:51], v[84:87], 0
	v_readlane_b32 s14, v252, 6
	v_readlane_b32 s15, v252, 7
	v_readlane_b32 s18, v252, 10
	v_readlane_b32 s19, v252, 11
	v_readlane_b32 s20, v252, 12
	v_readlane_b32 s21, v252, 13
	v_readlane_b32 s22, v252, 14
	s_waitcnt lgkmcnt(0)
	v_mfma_f32_32x32x16_bf16 v[48:63], v[88:91], v[80:83], v[48:63]
	ds_read_b128 v[88:91], v104 offset:64
	v_readlane_b32 s23, v252, 15
	s_waitcnt lgkmcnt(0)
	v_mfma_f32_32x32x16_bf16 v[32:47], v[88:91], v[76:79], v[32:47]
	ds_read_b128 v[88:91], v104 offset:6720
	ds_read_b128 v[126:129], v104 offset:96
	s_waitcnt lgkmcnt(1)
	v_mfma_f32_32x32x16_bf16 v[48:63], v[88:91], v[76:79], v[48:63]
	v_lshlrev_b64 v[88:89], 9, v[116:117]
	v_lshl_add_u64 v[88:89], v[110:111], 0, v[88:89]
	global_load_dwordx4 v[88:91], v[88:89], off
	s_nop 0
	global_load_dwordx4 v[96:99], v[92:93], off offset:1280
	s_nop 0
	global_load_dwordx4 v[92:95], v[118:119], off
	s_waitcnt lgkmcnt(0)
	v_mfma_f32_32x32x16_bf16 v[32:47], v[126:129], v[72:75], v[32:47]
	ds_read_b128 v[126:129], v104 offset:6752
	s_waitcnt lgkmcnt(0)
	v_mfma_f32_32x32x16_bf16 v[48:63], v[126:129], v[72:75], v[48:63]
	ds_read_b128 v[126:129], v104 offset:128
	s_waitcnt lgkmcnt(0)
	v_mfma_f32_32x32x16_bf16 v[32:47], v[126:129], v[68:71], v[32:47]
	ds_read_b128 v[126:129], v104 offset:6784
	s_waitcnt lgkmcnt(0)
	v_mfma_f32_32x32x16_bf16 v[48:63], v[126:129], v[68:71], v[48:63]
	ds_read_b128 v[126:129], v104 offset:6816
	s_waitcnt lgkmcnt(0)
	v_mfma_f32_32x32x16_bf16 v[48:63], v[126:129], v[64:67], v[48:63]
	ds_read_b128 v[126:129], v104 offset:160
	s_waitcnt lgkmcnt(0)
	v_mfma_f32_32x32x16_bf16 v[32:47], v[126:129], v[64:67], v[32:47]
	s_nop 8
	v_max_f32_e32 v104, v48, v48
	s_nop 1
	v_max_f32_e32 v105, v32, v32
	v_max_f32_e32 v104, v105, v104
	v_max3_f32 v104, v104, v33, v49
	v_add_f32_e32 v105, 0x41000000, v107
	v_max_f32_e32 v246, v34, v50
	v_max3_f32 v104, v104, v35, v51
	v_max3_f32 v246, v246, v36, v52
	v_max3_f32 v104, v104, v37, v53
	v_max3_f32 v246, v246, v38, v54
	v_max3_f32 v104, v104, v39, v55
	v_max3_f32 v246, v246, v40, v56
	v_max3_f32 v104, v104, v41, v57
	v_max3_f32 v246, v246, v42, v58
	v_max3_f32 v104, v104, v43, v59
	v_max3_f32 v246, v246, v44, v60
	v_max3_f32 v104, v104, v45, v61
	v_max3_f32 v246, v246, v46, v62
	v_max3_f32 v104, v104, v47, v63
	v_max_f32_e32 v104, v104, v246
	v_cmp_gt_f32_e32 vcc, v104, v105
	s_cbranch_vccz .LBB0_1574
	v_cmp_lt_i32_e32 vcc, v209, v208
	v_add_f32_e32 v104, 0, v104
	s_nop 0
	v_cndmask_b32_e32 v105, v207, v209, vcc
	v_lshlrev_b32_e32 v105, 2, v105
	ds_bpermute_b32 v105, v105, v104
	s_waitcnt lgkmcnt(0)
	v_max3_f32 v105, v107, v104, v105
	v_sub_f32_e32 v104, v107, v105
	v_exp_f32_e32 v104, v104
	v_mov_b32_e32 v107, v105
	v_mul_f32_e32 v109, v109, v104
	v_pk_mul_f32 v[14:15], v[14:15], v[104:105] op_sel_hi:[1,0]
	v_pk_mul_f32 v[12:13], v[12:13], v[104:105] op_sel_hi:[1,0]
	v_pk_mul_f32 v[10:11], v[10:11], v[104:105] op_sel_hi:[1,0]
	v_pk_mul_f32 v[8:9], v[8:9], v[104:105] op_sel_hi:[1,0]
	v_pk_mul_f32 v[6:7], v[6:7], v[104:105] op_sel_hi:[1,0]
	v_pk_mul_f32 v[4:5], v[4:5], v[104:105] op_sel_hi:[1,0]
	v_pk_mul_f32 v[2:3], v[2:3], v[104:105] op_sel_hi:[1,0]
	v_pk_mul_f32 v[0:1], v[0:1], v[104:105] op_sel_hi:[1,0]
	v_pk_mul_f32 v[30:31], v[30:31], v[104:105] op_sel_hi:[1,0]
	v_pk_mul_f32 v[28:29], v[28:29], v[104:105] op_sel_hi:[1,0]
	v_pk_mul_f32 v[26:27], v[26:27], v[104:105] op_sel_hi:[1,0]
	v_pk_mul_f32 v[24:25], v[24:25], v[104:105] op_sel_hi:[1,0]
	v_pk_mul_f32 v[22:23], v[22:23], v[104:105] op_sel_hi:[1,0]
	v_pk_mul_f32 v[20:21], v[20:21], v[104:105] op_sel_hi:[1,0]
	v_pk_mul_f32 v[18:19], v[18:19], v[104:105] op_sel_hi:[1,0]
	v_pk_mul_f32 v[16:17], v[16:17], v[104:105] op_sel_hi:[1,0]
	s_branch .LBB0_1574
